# static s_setprio 1 for waves 4-7 during P6 (HGRN2 chunk outputs)
# baseline (speedup 1.0000x reference)
; #define LAS __attribute__((address_space(3)))
; __global__ void __launch_bounds__(NT, 2) hymba_fwd(Args args) {
;     ...
;     if (IN(6)) {
;         const int d = tid & 127, seg = tid >> 7;
;         LAS float* SEG = (LAS float*)(lds + 4 * XB);
;         const float* og = args.in[8];
;         for (int item = bid; item < 512; item += G) {
.LBB0_1117:
	v_readlane_b32 s98, v237, 6
	s_nop 3
	s_cmp_ge_u32 s98, 4
	s_cbranch_scc0 .Lp6_prio_skip
	s_setprio 1

; __device__ __forceinline__ unsigned xb_ld(unsigned* p)              { return __hip_atomic_load(p, __ATOMIC_RELAXED, __HIP_MEMORY_SCOPE_AGENT); }
; __device__ __forceinline__ void xcd_barrier_complete(unsigned* bar, unsigned x, unsigned& nloc, unsigned& nx) {
;     const unsigned G = gridDim.x * gridDim.y * gridDim.z;
;     unsigned sum, cnt, mine, sp = 0u;
;     for (;;) {
;         sum = 0u; cnt = 0u; mine = 0u;
; #pragma unroll
;         for (unsigned j = 0; j < 16; ++j) { const unsigned c = xb_ld(&bar[XB_XCNT(j)]); sum += c; cnt += (c > 0u) ? 1u : 0u; mine = (j == x) ? c : mine; }
; __device__ __forceinline__ void xcd_barrier(const XcdBarrier& b) {
;     asm volatile("s_waitcnt vmcnt(0)" ::: "memory");
;     __syncthreads();
;     if (threadIdx.x == 0) {
;         unsigned* bar = b.bar;
;         __builtin_amdgcn_s_waitcnt(0);
;         unsigned nloc = b.st[0], nx = b.st[1];
;         if (nloc == 0u) { xcd_barrier_complete(bar, b.x, nloc, nx); b.st[0] = nloc; b.st[1] = nx; }
.LBB0_1194:
	s_setprio 0
	s_cmp_gt_i32 s77, 7
	v_readlane_b32 s2, v237, 52
	s_cselect_b64 s[0:1], -1, 0
	v_readlane_b32 s3, v237, 53
	s_and_b64 s[2:3], s[2:3], s[0:1]
	s_andn2_b64 vcc, exec, s[2:3]
	v_readlane_b32 s68, v237, 23
	v_readlane_b32 s69, v237, 24
	s_cbranch_vccnz .LBB0_1248
	s_waitcnt vmcnt(0)
	s_waitcnt vmcnt(0) lgkmcnt(0)
	s_barrier
	s_and_saveexec_b64 s[2:3], s[86:87]
	s_cbranch_execz .LBB0_1247
	s_add_i32 s4, 0, 0x23fc0
	v_mov_b32_e32 v0, s4
	s_waitcnt vmcnt(0) expcnt(0) lgkmcnt(0)
	ds_read_b32 v2, v0
	s_add_i32 s4, 0, 0x23fc4
	v_mov_b32_e32 v0, s4
	ds_read_b32 v0, v0
	s_waitcnt lgkmcnt(1)
	v_cmp_ne_u32_e32 vcc, 0, v2
	s_cbranch_vccnz .LBB0_1211
	v_readlane_b32 s4, v237, 0
	v_readlane_b32 s5, v237, 1
	s_mul_i32 s18, s5, s70
	v_readlane_b32 s10, v237, 4
	s_mul_i32 s18, s18, s4
	v_readlane_b32 s11, v237, 5
	s_add_u32 s4, s10, 0x1000
	s_addc_u32 s5, s11, 0
	s_add_u32 s6, s10, 0x1100
	s_addc_u32 s7, s11, 0
	s_add_u32 s8, s10, 0x1200
	s_addc_u32 s9, s11, 0
	s_add_u32 s10, s10, 0x1300
	s_addc_u32 s11, s11, 0
	s_mov_b32 s19, 1
	v_mov_b32_e32 v16, 0
	s_branch .LBB0_1199
